# head-group-1 attention pass: 128 sample items assigned statically to workgroups 0..127 (one per CU) instead of the dynamic queue, so no two busy workgroups share a CU
# baseline (speedup 1.0000x reference)
; #define LAS __attribute__((address_space(3)))
; DI unsigned xb_add(unsigned* p, unsigned v) { return __hip_atomic_fetch_add(p, v, __ATOMIC_RELAXED, __HIP_MEMORY_SCOPE_AGENT); }
; DI unsigned xb_xcc_id() { return (unsigned)__builtin_amdgcn_s_getreg((3 << 11) | 20) & 0xFu; }
; DI XcdBarrier xcd_barrier_post(unsigned* bar, volatile LAS unsigned* st) {
;   XcdBarrier b; b.bar = bar; b.x = xb_xcc_id(); b.st = st;
;   if (threadIdx.x == 0) (void)xb_add(&bar[XB_XCNT(b.x)], 1u);
;   return b;
; }
; __global__ void __launch_bounds__(256, 2) fwd_megakernel(Params p) {
;     ...
;   unsigned* bar = (unsigned*)launder(p.ws);
;   unsigned* qcnt = (unsigned*)(launder(p.ws) + W_QCNT);
;   if (threadIdx.x < 4) ((volatile unsigned*)(smem + SMEM_MAIN))[threadIdx.x] = 0u;
;   __syncthreads();
;   (void)xcd_barrier_post(bar, (volatile LAS unsigned*)(smem + SMEM_MAIN));
.LBB0_2:
	s_or_b64 exec, exec, s[0:1]
	s_waitcnt lgkmcnt(0)
	v_writelane_b32 v226, s48, 47
	v_writelane_b32 v226, s49, 48
	v_writelane_b32 v226, 0, 46
	v_writelane_b32 v226, 0, 51
	s_barrier
	s_getreg_b32 s8, hwreg(HW_REG_XCC_ID, 0, 4)
	v_cmp_eq_u32_e64 s[4:5], 0, v202
	v_mov_b64_e32 v[34:35], s[48:49]
	s_and_saveexec_b64 s[0:1], s[4:5]
	s_cbranch_execz .LBB0_6
	s_mov_b64 s[6:7], exec
	v_mbcnt_lo_u32_b32 v1, s6, 0
	v_mbcnt_hi_u32_b32 v1, s7, v1
	v_cmp_eq_u32_e32 vcc, 0, v1
	v_mov_b64_e32 v[34:35], s[48:49]
	s_and_saveexec_b64 s[2:3], vcc
	s_cbranch_execz .LBB0_5
	s_lshl_b32 s8, s8, 8
	s_and_b32 s8, s8, 0xf00
	s_bcnt1_i32_b64 s6, s[6:7]
	v_mov_b32_e32 v1, s8
	v_mov_b32_e32 v2, s6
	global_atomic_add v1, v2, s[48:49] offset:1024
	v_mov_b64_e32 v[34:35], s[48:49]

; DI void attn_phase_l0(const Params& p, int g, unsigned* qcnt, char* smem) {
;     ...
;     if (threadIdx.x == 0) {
;       int item = -1;
;       while (hoff < 8) {
;         const int hd_ = (h0 + hoff) & 7;
;         const unsigned k_ = atomicAdd(qcnt + 8 + hd_, 1u);
;         if (k_ < 128u) { item = (int)k_ * 8 + hd_; break; }
;         hoff++;
;       }
;       if (item < 0) item = n_mla_p + (int)atomicAdd(qcnt, 1u);
;       *qslot = item;
;     }
;     __syncthreads();
;     const int it = *qslot;
;     if (it >= total) break;
.LBB0_634:
	s_or_b64 exec, exec, s[8:9]
	s_waitcnt vmcnt(0)
	v_readfirstlane_b32 s8, v2
	s_cmp_lg_u32 s74, 0
	s_cbranch_scc1 .Lq1_dyn
	s_cmpk_lg_u32 s50, 0x200
	s_cbranch_scc1 .Lq1_dyn
	v_readlane_b32 s98, v226, 51
	s_mov_b32 s8, s75
	s_add_u32 s99, s98, 1
	v_writelane_b32 v226, s99, 51
	s_cmp_lg_u32 s98, 0
	s_cbranch_scc1 .Lq1_dyn
	s_cmpk_lt_u32 s78, 0x80
	s_cselect_b32 s8, s78, s75
.Lq1_dyn:
	s_add_i32 s8, s74, s8
	s_nop 0
	v_add_u32_e32 v4, s8, v0
